# FFN-up macro-tile loop pass-major: each 64-deep k-chunk is consumed in four weight-column passes with fragments refreshed in place, so all operand rows are requested as whole 128-byte lines (6 LDS slo
# speedup vs baseline: 1.0394x; 1.0394x over previous
.LBB0_2769:
	v_readlane_b32 s2, v246, 26
	s_cmp_eq_u32 s2, 10
	s_cselect_b64 s[8:9], -1, 0
	s_load_dwordx2 s[10:11], s[0:1], 0x108
	v_cndmask_b32_e64 v0, 0, 1, s[8:9]
	s_mov_b32 s2, s83
	v_readfirstlane_b32 s0, v0
	s_or_b32 s0, s58, s0
	s_mul_hi_i32 s1, s0, 0xb00000
	s_mul_i32 s0, s0, 0xb00000
	s_waitcnt lgkmcnt(0)
	s_add_u32 s0, s10, s0
	s_addc_u32 s1, s11, s1
	s_add_u32 s0, s0, 0x7c78100
	s_addc_u32 s1, s1, 0
	s_add_u32 s8, s10, 0x3000000
	s_addc_u32 s9, s11, 0
	s_add_u32 s10, s10, 0x14958100
	s_addc_u32 s11, s11, 0
	s_mov_b32 s14, 0x10000
	v_and_b32_e32 v171, 63, v194
	v_lshrrev_b32_e32 v172, 6, v194
	v_lshrrev_b32_e32 v160, 2, v194
	v_lshlrev_b32_e32 v160, 11, v160
	v_and_b32_e32 v173, 3, v171
	v_bfe_u32 v174, v171, 4, 2
	v_xor_b32_e32 v173, v173, v174
	v_lshl_add_u32 v160, v173, 4, v160
	v_add_u32_e32 v161, 0x20000, v160
	v_and_b32_e32 v175, 31, v171
	v_lshrrev_b32_e32 v176, 5, v171
	v_bfe_u32 v177, v175, 2, 2
	v_xor_b32_e32 v178, v176, v177
	v_xor_b32_e32 v179, 2, v178
	v_lshrrev_b32_e32 v180, 1, v172
	v_and_b32_e32 v181, 1, v172
	v_lshl_add_u32 v182, v180, 6, v175
	v_lshl_add_u32 v183, v181, 6, v175
	v_lshlrev_b32_e32 v182, 6, v182
	v_lshlrev_b32_e32 v183, 6, v183
	v_lshl_add_u32 v154, v178, 4, v182
	v_lshl_add_u32 v155, v179, 4, v182
	v_lshl_add_u32 v156, v178, 4, v183
	v_lshl_add_u32 v157, v179, 4, v183
	v_add_u32_e32 v158, 0x2000, v156
	v_add_u32_e32 v159, 0x2000, v157
	v_lshlrev_b32_e32 v184, 6, v180
	v_lshl_add_u32 v184, v176, 2, v184
	v_mul_u32_u24_e32 v184, 0x1600, v184
	v_lshl_add_u32 v185, v181, 5, v175
	v_lshl_add_u32 v162, v185, 1, v184
	v_add_u32_e32 v163, 0x1600, v162
	v_add_u32_e32 v164, 0x2c00, v162
	v_add_u32_e32 v165, 0x4200, v162
	v_lshrrev_b32_e32 v173, 3, v171
	v_lshl_add_u32 v173, v172, 3, v173
	v_lshlrev_b32_e32 v173, 11, v173
	v_and_b32_e32 v174, 1, v172
	v_lshrrev_b32_e32 v177, 4, v171
	v_lshl_add_u32 v174, v174, 2, v177
	v_and_b32_e32 v177, 7, v171
	v_xor_b32_e32 v174, v174, v177
	v_lshl_add_u32 v249, v174, 4, v173
	v_add_u32_e32 v254, 0x20000, v249
	v_add_u32_e32 v166, 0x10000, v249
	v_add_u32_e32 v167, 0x30000, v249
	v_bfe_u32 v177, v175, 1, 3
	v_or_b32_e32 v174, 0, v176
	v_xor_b32_e32 v174, v174, v177
	v_lshlrev_b32_e32 v174, 4, v174
	v_lshl_add_u32 v173, v180, 5, v175
	v_lshl_add_u32 v168, v173, 7, v174
	v_lshl_add_u32 v173, v181, 5, v175
	v_lshl_add_u32 v238, v173, 7, v174
	v_or_b32_e32 v174, 2, v176
	v_xor_b32_e32 v174, v174, v177
	v_lshlrev_b32_e32 v174, 4, v174
	v_lshl_add_u32 v173, v180, 5, v175
	v_lshl_add_u32 v169, v173, 7, v174
	v_lshl_add_u32 v173, v181, 5, v175
	v_lshl_add_u32 v239, v173, 7, v174
	v_or_b32_e32 v174, 4, v176
	v_xor_b32_e32 v174, v174, v177
	v_lshlrev_b32_e32 v174, 4, v174
	v_lshl_add_u32 v173, v180, 5, v175
	v_lshl_add_u32 v236, v173, 7, v174
	v_lshl_add_u32 v173, v181, 5, v175
	v_lshl_add_u32 v240, v173, 7, v174
	v_or_b32_e32 v174, 6, v176
	v_xor_b32_e32 v174, v174, v177
	v_lshlrev_b32_e32 v174, 4, v174
	v_lshl_add_u32 v173, v180, 5, v175
	v_lshl_add_u32 v237, v173, 7, v174
	v_lshl_add_u32 v173, v181, 5, v175
	v_lshl_add_u32 v241, v173, 7, v174
	v_readfirstlane_b32 s65, v194
	s_nop 0
	s_lshl_b32 s65, s65, 4
	s_add_u32 s65, s65, 16
	v_readlane_b32 s62, v246, 14
	s_mov_b32 s64, 0

.Lhw_ffnup_dloop:
	s_cmp_ge_u32 s2, s64
	s_cbranch_scc1 .Lhw_ffnup_tail
	s_mul_i32 s6, s2, 745
	s_lshr_b32 s6, s6, 16
	s_mul_i32 s14, s6, 88
	s_sub_i32 s14, s2, s14
	v_readlane_b32 s13, v246, 16
	s_lshl_b32 s6, s6, 2
	s_and_b32 s12, s14, 3
	s_add_i32 s6, s6, s12
	s_add_i32 s6, s6, s13
	s_lshl_b32 s6, s6, 7
	s_lshr_b32 s14, s14, 2
	s_lshl_b32 s14, s14, 8
	s_lshl_b32 vcc_lo, s6, 11
	s_add_u32 s66, s10, vcc_lo
	s_addc_u32 s67, s11, 0
	s_lshl_b32 vcc_lo, s14, 11
	s_add_u32 s12, s0, vcc_lo
	s_addc_u32 s13, s1, 0
	s_add_u32 s62, s12, 0x40000
	s_addc_u32 s63, s13, 0
	s_barrier
	s_add_u32 m0, s65, 0x6000
	s_nop 0
	global_load_lds_dwordx4 v249, s[12:13]
	s_add_u32 m0, s65, 0x7000
	s_nop 0
	global_load_lds_dwordx4 v254, s[12:13]
	s_add_u32 m0, s65, 0x8000
	s_nop 0
	global_load_lds_dwordx4 v249, s[66:67]
	s_add_u32 m0, s65, 0x9000
	s_nop 0
	global_load_lds_dwordx4 v254, s[66:67]
	s_add_u32 m0, s65, 0xa000
	s_nop 0
	global_load_lds_dwordx4 v166, s[66:67]
	s_add_u32 m0, s65, 0xb000
	s_nop 0
	global_load_lds_dwordx4 v167, s[66:67]
	s_add_u32 m0, s65, 0x0
	s_nop 0
	global_load_lds_dwordx4 v166, s[12:13]
	s_add_u32 m0, s65, 0x1000
	s_nop 0
	global_load_lds_dwordx4 v167, s[12:13]
	s_add_u32 m0, s65, 0x2000
	s_nop 0
	global_load_lds_dwordx4 v249, s[62:63]
	s_add_u32 m0, s65, 0x3000
	s_nop 0
	global_load_lds_dwordx4 v254, s[62:63]
	v_mov_b32_e32 v2, 0
	v_mov_b32_e32 v3, 0
	v_mov_b32_e32 v4, 0
	v_mov_b32_e32 v5, 0
	v_mov_b32_e32 v6, 0
	v_mov_b32_e32 v7, 0
	v_mov_b32_e32 v8, 0
	v_mov_b32_e32 v9, 0
	v_mov_b32_e32 v10, 0
	v_mov_b32_e32 v11, 0
	v_mov_b32_e32 v12, 0
	v_mov_b32_e32 v13, 0
	v_mov_b32_e32 v14, 0
	v_mov_b32_e32 v15, 0
	v_mov_b32_e32 v16, 0
	v_mov_b32_e32 v17, 0
	v_mov_b32_e32 v18, 0
	v_mov_b32_e32 v19, 0
	v_mov_b32_e32 v20, 0
	v_mov_b32_e32 v21, 0
	v_mov_b32_e32 v22, 0
	v_mov_b32_e32 v23, 0
	v_mov_b32_e32 v24, 0
	v_mov_b32_e32 v25, 0
	v_mov_b32_e32 v26, 0
	v_mov_b32_e32 v27, 0
	v_mov_b32_e32 v28, 0
	v_mov_b32_e32 v29, 0
	v_mov_b32_e32 v30, 0
	v_mov_b32_e32 v31, 0
	v_mov_b32_e32 v32, 0
	v_mov_b32_e32 v33, 0
	v_mov_b32_e32 v34, 0
	v_mov_b32_e32 v35, 0
	v_mov_b32_e32 v36, 0
	v_mov_b32_e32 v37, 0
	v_mov_b32_e32 v38, 0
	v_mov_b32_e32 v39, 0
	v_mov_b32_e32 v40, 0
	v_mov_b32_e32 v41, 0
	v_mov_b32_e32 v42, 0
	v_mov_b32_e32 v43, 0
	v_mov_b32_e32 v44, 0
	v_mov_b32_e32 v45, 0
	v_mov_b32_e32 v46, 0
	v_mov_b32_e32 v47, 0
	v_mov_b32_e32 v48, 0
	v_mov_b32_e32 v49, 0
	v_mov_b32_e32 v50, 0
	v_mov_b32_e32 v51, 0
	v_mov_b32_e32 v52, 0
	v_mov_b32_e32 v53, 0
	v_mov_b32_e32 v54, 0
	v_mov_b32_e32 v55, 0
	v_mov_b32_e32 v56, 0
	v_mov_b32_e32 v57, 0
	v_mov_b32_e32 v58, 0
	v_mov_b32_e32 v59, 0
	v_mov_b32_e32 v60, 0
	v_mov_b32_e32 v61, 0
	v_mov_b32_e32 v62, 0
	v_mov_b32_e32 v63, 0
	v_mov_b32_e32 v64, 0
	v_mov_b32_e32 v65, 0
	v_mov_b32_e32 v66, 0
	v_mov_b32_e32 v67, 0
	v_mov_b32_e32 v68, 0
	v_mov_b32_e32 v69, 0
	v_mov_b32_e32 v70, 0
	v_mov_b32_e32 v71, 0
	v_mov_b32_e32 v72, 0
	v_mov_b32_e32 v73, 0
	v_mov_b32_e32 v74, 0
	v_mov_b32_e32 v75, 0
	v_mov_b32_e32 v76, 0
	v_mov_b32_e32 v77, 0
	v_mov_b32_e32 v78, 0
	v_mov_b32_e32 v79, 0
	v_mov_b32_e32 v80, 0
	v_mov_b32_e32 v81, 0
	v_mov_b32_e32 v82, 0
	v_mov_b32_e32 v83, 0
	v_mov_b32_e32 v84, 0
	v_mov_b32_e32 v85, 0
	v_mov_b32_e32 v86, 0
	v_mov_b32_e32 v87, 0
	v_mov_b32_e32 v88, 0
	v_mov_b32_e32 v89, 0
	v_mov_b32_e32 v90, 0
	v_mov_b32_e32 v91, 0
	v_mov_b32_e32 v92, 0
	v_mov_b32_e32 v93, 0
	v_mov_b32_e32 v94, 0
	v_mov_b32_e32 v95, 0
	v_mov_b32_e32 v96, 0
	v_mov_b32_e32 v97, 0
	v_mov_b32_e32 v98, 0
	v_mov_b32_e32 v99, 0
	v_mov_b32_e32 v100, 0
	v_mov_b32_e32 v101, 0
	v_mov_b32_e32 v102, 0
	v_mov_b32_e32 v103, 0
	v_mov_b32_e32 v104, 0
	v_mov_b32_e32 v105, 0
	v_mov_b32_e32 v106, 0
	v_mov_b32_e32 v107, 0
	v_mov_b32_e32 v108, 0
	v_mov_b32_e32 v109, 0
	v_mov_b32_e32 v110, 0
	v_mov_b32_e32 v111, 0
	v_mov_b32_e32 v112, 0
	v_mov_b32_e32 v113, 0
	v_mov_b32_e32 v114, 0
	v_mov_b32_e32 v115, 0
	v_mov_b32_e32 v116, 0
	v_mov_b32_e32 v117, 0
	v_mov_b32_e32 v118, 0
	v_mov_b32_e32 v119, 0
	v_mov_b32_e32 v120, 0
	v_mov_b32_e32 v121, 0
	v_mov_b32_e32 v122, 0
	v_mov_b32_e32 v123, 0
	v_mov_b32_e32 v124, 0
	v_mov_b32_e32 v125, 0
	v_mov_b32_e32 v126, 0
	v_mov_b32_e32 v127, 0
	v_mov_b32_e32 v128, 0
	v_mov_b32_e32 v129, 0
	s_waitcnt vmcnt(0)
	s_barrier
	ds_read_b128 v[130:133], v168 offset:32784
	ds_read_b128 v[146:149], v168 offset:40976
	ds_read_b128 v[220:223], v238 offset:24592
	ds_read_b128 v[134:137], v169 offset:32784
	ds_read_b128 v[150:153], v169 offset:40976
	ds_read_b128 v[224:227], v239 offset:24592
	ds_read_b128 v[138:141], v236 offset:32784
	ds_read_b128 v[212:215], v236 offset:40976
	ds_read_b128 v[228:231], v240 offset:24592
	ds_read_b128 v[142:145], v237 offset:32784
	ds_read_b128 v[216:219], v237 offset:40976
	ds_read_b128 v[232:235], v241 offset:24592
	s_waitcnt lgkmcnt(0)
	s_barrier
	s_mov_b32 s59, 15
.Lhw_ffnup_d_loop:
	v_mfma_f32_32x32x16_bf16 v[2:17], v[130:133], v[220:223], v[2:17]
	s_add_u32 m0, s65, 0x4000
	s_nop 0
	global_load_lds_dwordx4 v166, s[62:63]
	v_mfma_f32_32x32x16_bf16 v[34:49], v[146:149], v[220:223], v[34:49]
	s_add_u32 m0, s65, 0x5000
	ds_read_b128 v[220:223], v238 offset:16
	global_load_lds_dwordx4 v167, s[62:63]
	v_mfma_f32_32x32x16_bf16 v[2:17], v[134:137], v[224:227], v[2:17]
	s_add_u32 s12, s12, 128
	s_addc_u32 s13, s13, 0
	s_add_u32 s66, s66, 128
	s_addc_u32 s67, s67, 0
	v_mfma_f32_32x32x16_bf16 v[34:49], v[150:153], v[224:227], v[34:49]
	s_add_u32 m0, s65, 0x6000
	ds_read_b128 v[224:227], v239 offset:16
	global_load_lds_dwordx4 v249, s[12:13]
	v_mfma_f32_32x32x16_bf16 v[2:17], v[138:141], v[228:231], v[2:17]
	s_add_u32 m0, s65, 0x7000
	s_nop 0
	global_load_lds_dwordx4 v254, s[12:13]
	v_mfma_f32_32x32x16_bf16 v[34:49], v[212:215], v[228:231], v[34:49]
	s_add_u32 m0, s65, 0x8000
	ds_read_b128 v[228:231], v240 offset:16
	global_load_lds_dwordx4 v249, s[66:67]
	v_mfma_f32_32x32x16_bf16 v[2:17], v[142:145], v[232:235], v[2:17]
	s_add_u32 m0, s65, 0x9000
	s_nop 0
	global_load_lds_dwordx4 v254, s[66:67]
	v_mfma_f32_32x32x16_bf16 v[34:49], v[216:219], v[232:235], v[34:49]
	s_add_u32 m0, s65, 0xa000
	ds_read_b128 v[232:235], v241 offset:16
	global_load_lds_dwordx4 v166, s[66:67]
	s_waitcnt lgkmcnt(3)
	v_mfma_f32_32x32x16_bf16 v[18:33], v[130:133], v[220:223], v[18:33]
	s_add_u32 m0, s65, 0xb000
	s_nop 0
	global_load_lds_dwordx4 v167, s[66:67]
	v_mfma_f32_32x32x16_bf16 v[50:65], v[146:149], v[220:223], v[50:65]
	ds_read_b128 v[220:223], v238 offset:8208
	s_waitcnt lgkmcnt(3)
	v_mfma_f32_32x32x16_bf16 v[18:33], v[134:137], v[224:227], v[18:33]
	v_mfma_f32_32x32x16_bf16 v[50:65], v[150:153], v[224:227], v[50:65]
	ds_read_b128 v[224:227], v239 offset:8208
	s_waitcnt lgkmcnt(3)
	v_mfma_f32_32x32x16_bf16 v[18:33], v[138:141], v[228:231], v[18:33]
	v_mfma_f32_32x32x16_bf16 v[50:65], v[212:215], v[228:231], v[50:65]
	ds_read_b128 v[228:231], v240 offset:8208
	s_waitcnt lgkmcnt(3)
	v_mfma_f32_32x32x16_bf16 v[18:33], v[142:145], v[232:235], v[18:33]
	v_mfma_f32_32x32x16_bf16 v[50:65], v[216:219], v[232:235], v[50:65]
	ds_read_b128 v[232:235], v241 offset:8208
	s_waitcnt vmcnt(0) lgkmcnt(0)
	s_barrier
	v_mfma_f32_32x32x16_bf16 v[66:81], v[130:133], v[220:223], v[66:81]
	s_add_u32 s62, s62, 128
	s_addc_u32 s63, s63, 0
	v_mfma_f32_32x32x16_bf16 v[98:113], v[146:149], v[220:223], v[98:113]
	s_add_u32 m0, s65, 0x0
	ds_read_b128 v[220:223], v238 offset:16400
	global_load_lds_dwordx4 v166, s[12:13]
	v_mfma_f32_32x32x16_bf16 v[66:81], v[134:137], v[224:227], v[66:81]
	s_add_u32 m0, s65, 0x1000
	s_nop 0
	global_load_lds_dwordx4 v167, s[12:13]
	v_mfma_f32_32x32x16_bf16 v[98:113], v[150:153], v[224:227], v[98:113]
	s_add_u32 m0, s65, 0x2000
	ds_read_b128 v[224:227], v239 offset:16400
	global_load_lds_dwordx4 v249, s[62:63]
	v_mfma_f32_32x32x16_bf16 v[66:81], v[138:141], v[228:231], v[66:81]
	s_add_u32 m0, s65, 0x3000
	s_nop 0
	global_load_lds_dwordx4 v254, s[62:63]
	v_mfma_f32_32x32x16_bf16 v[98:113], v[212:215], v[228:231], v[98:113]
	ds_read_b128 v[228:231], v240 offset:16400
	v_mfma_f32_32x32x16_bf16 v[66:81], v[142:145], v[232:235], v[66:81]
	v_mfma_f32_32x32x16_bf16 v[98:113], v[216:219], v[232:235], v[98:113]
	ds_read_b128 v[232:235], v241 offset:16400
	s_waitcnt lgkmcnt(3)
	v_mfma_f32_32x32x16_bf16 v[82:97], v[130:133], v[220:223], v[82:97]
	ds_read_b128 v[130:133], v168 offset:32784
	v_mfma_f32_32x32x16_bf16 v[114:129], v[146:149], v[220:223], v[114:129]
	ds_read_b128 v[220:223], v238 offset:24592
	ds_read_b128 v[146:149], v168 offset:40976
	s_waitcnt lgkmcnt(5)
	v_mfma_f32_32x32x16_bf16 v[82:97], v[134:137], v[224:227], v[82:97]
	ds_read_b128 v[134:137], v169 offset:32784
	v_mfma_f32_32x32x16_bf16 v[114:129], v[150:153], v[224:227], v[114:129]
	ds_read_b128 v[224:227], v239 offset:24592
	ds_read_b128 v[150:153], v169 offset:40976
	s_waitcnt lgkmcnt(7)
	v_mfma_f32_32x32x16_bf16 v[82:97], v[138:141], v[228:231], v[82:97]
	ds_read_b128 v[138:141], v236 offset:32784
	v_mfma_f32_32x32x16_bf16 v[114:129], v[212:215], v[228:231], v[114:129]
	ds_read_b128 v[228:231], v240 offset:24592
	ds_read_b128 v[212:215], v236 offset:40976
	s_waitcnt lgkmcnt(9)
	v_mfma_f32_32x32x16_bf16 v[82:97], v[142:145], v[232:235], v[82:97]
	ds_read_b128 v[142:145], v237 offset:32784
	v_mfma_f32_32x32x16_bf16 v[114:129], v[216:219], v[232:235], v[114:129]
	ds_read_b128 v[232:235], v241 offset:24592
	ds_read_b128 v[216:219], v237 offset:40976
	s_waitcnt vmcnt(0) lgkmcnt(0)
	s_barrier
	s_sub_u32 s59, s59, 1
	s_cmp_lg_u32 s59, 0
	s_cbranch_scc1 .Lhw_ffnup_d_loop
	v_mfma_f32_32x32x16_bf16 v[2:17], v[130:133], v[220:223], v[2:17]
	s_add_u32 m0, s65, 0x4000
	s_nop 0
	global_load_lds_dwordx4 v166, s[62:63]
	v_mfma_f32_32x32x16_bf16 v[34:49], v[146:149], v[220:223], v[34:49]
	s_add_u32 m0, s65, 0x5000
	ds_read_b128 v[220:223], v238 offset:16
	global_load_lds_dwordx4 v167, s[62:63]
	v_mfma_f32_32x32x16_bf16 v[2:17], v[134:137], v[224:227], v[2:17]
	v_mfma_f32_32x32x16_bf16 v[34:49], v[150:153], v[224:227], v[34:49]
	ds_read_b128 v[224:227], v239 offset:16
	v_mfma_f32_32x32x16_bf16 v[2:17], v[138:141], v[228:231], v[2:17]
	v_mfma_f32_32x32x16_bf16 v[34:49], v[212:215], v[228:231], v[34:49]
	ds_read_b128 v[228:231], v240 offset:16
	v_mfma_f32_32x32x16_bf16 v[2:17], v[142:145], v[232:235], v[2:17]
	v_mfma_f32_32x32x16_bf16 v[34:49], v[216:219], v[232:235], v[34:49]
	ds_read_b128 v[232:235], v241 offset:16
	s_waitcnt lgkmcnt(3)
	v_mfma_f32_32x32x16_bf16 v[18:33], v[130:133], v[220:223], v[18:33]
	v_mfma_f32_32x32x16_bf16 v[50:65], v[146:149], v[220:223], v[50:65]
	ds_read_b128 v[220:223], v238 offset:8208
	s_waitcnt lgkmcnt(3)
	v_mfma_f32_32x32x16_bf16 v[18:33], v[134:137], v[224:227], v[18:33]
	v_mfma_f32_32x32x16_bf16 v[50:65], v[150:153], v[224:227], v[50:65]
	ds_read_b128 v[224:227], v239 offset:8208
	s_waitcnt lgkmcnt(3)
	v_mfma_f32_32x32x16_bf16 v[18:33], v[138:141], v[228:231], v[18:33]
	v_mfma_f32_32x32x16_bf16 v[50:65], v[212:215], v[228:231], v[50:65]
	ds_read_b128 v[228:231], v240 offset:8208
	s_waitcnt lgkmcnt(3)
	v_mfma_f32_32x32x16_bf16 v[18:33], v[142:145], v[232:235], v[18:33]
	v_mfma_f32_32x32x16_bf16 v[50:65], v[216:219], v[232:235], v[50:65]
	ds_read_b128 v[232:235], v241 offset:8208
	s_waitcnt vmcnt(0) lgkmcnt(0)
	s_barrier
	v_mfma_f32_32x32x16_bf16 v[66:81], v[130:133], v[220:223], v[66:81]
	v_mfma_f32_32x32x16_bf16 v[98:113], v[146:149], v[220:223], v[98:113]
	ds_read_b128 v[220:223], v238 offset:16400
	v_mfma_f32_32x32x16_bf16 v[66:81], v[134:137], v[224:227], v[66:81]
	v_mfma_f32_32x32x16_bf16 v[98:113], v[150:153], v[224:227], v[98:113]
	ds_read_b128 v[224:227], v239 offset:16400
	v_mfma_f32_32x32x16_bf16 v[66:81], v[138:141], v[228:231], v[66:81]
	v_mfma_f32_32x32x16_bf16 v[98:113], v[212:215], v[228:231], v[98:113]
	ds_read_b128 v[228:231], v240 offset:16400
	v_mfma_f32_32x32x16_bf16 v[66:81], v[142:145], v[232:235], v[66:81]
	v_mfma_f32_32x32x16_bf16 v[98:113], v[216:219], v[232:235], v[98:113]
	ds_read_b128 v[232:235], v241 offset:16400
	s_waitcnt lgkmcnt(3)
	v_mfma_f32_32x32x16_bf16 v[82:97], v[130:133], v[220:223], v[82:97]
	v_mfma_f32_32x32x16_bf16 v[114:129], v[146:149], v[220:223], v[114:129]
	s_waitcnt lgkmcnt(2)
	v_mfma_f32_32x32x16_bf16 v[82:97], v[134:137], v[224:227], v[82:97]
	v_mfma_f32_32x32x16_bf16 v[114:129], v[150:153], v[224:227], v[114:129]
	s_waitcnt lgkmcnt(1)
	v_mfma_f32_32x32x16_bf16 v[82:97], v[138:141], v[228:231], v[82:97]
	v_mfma_f32_32x32x16_bf16 v[114:129], v[212:215], v[228:231], v[114:129]
	s_waitcnt lgkmcnt(0)
	v_mfma_f32_32x32x16_bf16 v[82:97], v[142:145], v[232:235], v[82:97]
	v_mfma_f32_32x32x16_bf16 v[114:129], v[216:219], v[232:235], v[114:129]
	s_nop 7
	s_nop 7
	s_mul_i32 vcc_lo, s6, 0x1600
	s_add_u32 s66, s8, vcc_lo
	s_addc_u32 s67, s9, 0
	s_add_u32 s66, s66, s14
	s_addc_u32 s67, s67, 0
	v_mul_f32_e32 v171, 0xbfb8aa3b, v2
	v_mul_f32_e32 v172, 0xbfb8aa3b, v3
	v_mul_f32_e32 v173, 0xbfb8aa3b, v4
	v_mul_f32_e32 v174, 0xbfb8aa3b, v5
	v_exp_f32_e32 v171, v171
	v_exp_f32_e32 v172, v172
	v_exp_f32_e32 v173, v173
	v_exp_f32_e32 v174, v174
	s_nop 0
	v_add_f32_e32 v171, 1.0, v171
	v_add_f32_e32 v172, 1.0, v172
	v_add_f32_e32 v173, 1.0, v173
	v_add_f32_e32 v174, 1.0, v174
	v_rcp_f32_e32 v171, v171
	v_rcp_f32_e32 v172, v172
	v_rcp_f32_e32 v173, v173
	v_rcp_f32_e32 v174, v174
	s_nop 0
	v_mul_f32_e32 v171, v2, v171
	v_mul_f32_e32 v172, v3, v172
	v_mul_f32_e32 v173, v4, v173
	v_mul_f32_e32 v174, v5, v174
	v_mul_f32_e32 v171, v18, v171
	v_mul_f32_e32 v172, v19, v172
	v_mul_f32_e32 v173, v20, v173
	v_mul_f32_e32 v174, v21, v174
	v_cvt_pk_bf16_f32 v179, v171, v171
	v_cvt_pk_bf16_f32 v180, v172, v172
	v_cvt_pk_bf16_f32 v181, v173, v173
	v_cvt_pk_bf16_f32 v182, v174, v174
	global_store_short v162, v179, s[66:67]
	global_store_short v163, v180, s[66:67]
	global_store_short v164, v181, s[66:67]
	global_store_short v165, v182, s[66:67]
	s_add_u32 s66, s66, 0xb000
	s_addc_u32 s67, s67, 0
	v_mul_f32_e32 v171, 0xbfb8aa3b, v6
	v_mul_f32_e32 v172, 0xbfb8aa3b, v7
	v_mul_f32_e32 v173, 0xbfb8aa3b, v8
	v_mul_f32_e32 v174, 0xbfb8aa3b, v9
	v_exp_f32_e32 v171, v171
	v_exp_f32_e32 v172, v172
	v_exp_f32_e32 v173, v173
	v_exp_f32_e32 v174, v174
	s_nop 0
	v_add_f32_e32 v171, 1.0, v171
	v_add_f32_e32 v172, 1.0, v172
	v_add_f32_e32 v173, 1.0, v173
	v_add_f32_e32 v174, 1.0, v174
	v_rcp_f32_e32 v171, v171
	v_rcp_f32_e32 v172, v172
	v_rcp_f32_e32 v173, v173
	v_rcp_f32_e32 v174, v174
	s_nop 0
	v_mul_f32_e32 v171, v6, v171
	v_mul_f32_e32 v172, v7, v172
	v_mul_f32_e32 v173, v8, v173
	v_mul_f32_e32 v174, v9, v174
	v_mul_f32_e32 v171, v22, v171
	v_mul_f32_e32 v172, v23, v172
	v_mul_f32_e32 v173, v24, v173
	v_mul_f32_e32 v174, v25, v174
	v_cvt_pk_bf16_f32 v179, v171, v171
	v_cvt_pk_bf16_f32 v180, v172, v172
	v_cvt_pk_bf16_f32 v181, v173, v173
	v_cvt_pk_bf16_f32 v182, v174, v174
	global_store_short v162, v179, s[66:67]
	global_store_short v163, v180, s[66:67]
	global_store_short v164, v181, s[66:67]
	global_store_short v165, v182, s[66:67]
	s_add_u32 s66, s66, 0xb000
	s_addc_u32 s67, s67, 0
	v_mul_f32_e32 v171, 0xbfb8aa3b, v10
	v_mul_f32_e32 v172, 0xbfb8aa3b, v11
	v_mul_f32_e32 v173, 0xbfb8aa3b, v12
	v_mul_f32_e32 v174, 0xbfb8aa3b, v13
	v_exp_f32_e32 v171, v171
	v_exp_f32_e32 v172, v172
	v_exp_f32_e32 v173, v173
	v_exp_f32_e32 v174, v174
	s_nop 0
	v_add_f32_e32 v171, 1.0, v171
	v_add_f32_e32 v172, 1.0, v172
	v_add_f32_e32 v173, 1.0, v173
	v_add_f32_e32 v174, 1.0, v174
	v_rcp_f32_e32 v171, v171
	v_rcp_f32_e32 v172, v172
	v_rcp_f32_e32 v173, v173
	v_rcp_f32_e32 v174, v174
	s_nop 0
	v_mul_f32_e32 v171, v10, v171
	v_mul_f32_e32 v172, v11, v172
	v_mul_f32_e32 v173, v12, v173
	v_mul_f32_e32 v174, v13, v174
	v_mul_f32_e32 v171, v26, v171
	v_mul_f32_e32 v172, v27, v172
	v_mul_f32_e32 v173, v28, v173
	v_mul_f32_e32 v174, v29, v174
	v_cvt_pk_bf16_f32 v179, v171, v171
	v_cvt_pk_bf16_f32 v180, v172, v172
	v_cvt_pk_bf16_f32 v181, v173, v173
	v_cvt_pk_bf16_f32 v182, v174, v174
	global_store_short v162, v179, s[66:67]
	global_store_short v163, v180, s[66:67]
	global_store_short v164, v181, s[66:67]
	global_store_short v165, v182, s[66:67]
	s_add_u32 s66, s66, 0xb000
	s_addc_u32 s67, s67, 0
	v_mul_f32_e32 v171, 0xbfb8aa3b, v14
	v_mul_f32_e32 v172, 0xbfb8aa3b, v15
	v_mul_f32_e32 v173, 0xbfb8aa3b, v16
	v_mul_f32_e32 v174, 0xbfb8aa3b, v17
	v_exp_f32_e32 v171, v171
	v_exp_f32_e32 v172, v172
	v_exp_f32_e32 v173, v173
	v_exp_f32_e32 v174, v174
	s_nop 0
	v_add_f32_e32 v171, 1.0, v171
	v_add_f32_e32 v172, 1.0, v172
	v_add_f32_e32 v173, 1.0, v173
	v_add_f32_e32 v174, 1.0, v174
	v_rcp_f32_e32 v171, v171
	v_rcp_f32_e32 v172, v172
	v_rcp_f32_e32 v173, v173
	v_rcp_f32_e32 v174, v174
	s_nop 0
	v_mul_f32_e32 v171, v14, v171
	v_mul_f32_e32 v172, v15, v172
	v_mul_f32_e32 v173, v16, v173
	v_mul_f32_e32 v174, v17, v174
	v_mul_f32_e32 v171, v30, v171
	v_mul_f32_e32 v172, v31, v172
	v_mul_f32_e32 v173, v32, v173
	v_mul_f32_e32 v174, v33, v174
	v_cvt_pk_bf16_f32 v179, v171, v171
	v_cvt_pk_bf16_f32 v180, v172, v172
	v_cvt_pk_bf16_f32 v181, v173, v173
	v_cvt_pk_bf16_f32 v182, v174, v174
	global_store_short v162, v179, s[66:67]
	global_store_short v163, v180, s[66:67]
	global_store_short v164, v181, s[66:67]
	global_store_short v165, v182, s[66:67]
	s_add_u32 s66, s66, 0xb000
	s_addc_u32 s67, s67, 0
	v_mul_f32_e32 v171, 0xbfb8aa3b, v34
	v_mul_f32_e32 v172, 0xbfb8aa3b, v35
	v_mul_f32_e32 v173, 0xbfb8aa3b, v36
	v_mul_f32_e32 v174, 0xbfb8aa3b, v37
	v_exp_f32_e32 v171, v171
	v_exp_f32_e32 v172, v172
	v_exp_f32_e32 v173, v173
	v_exp_f32_e32 v174, v174
	s_nop 0
	v_add_f32_e32 v171, 1.0, v171
	v_add_f32_e32 v172, 1.0, v172
	v_add_f32_e32 v173, 1.0, v173
	v_add_f32_e32 v174, 1.0, v174
	v_rcp_f32_e32 v171, v171
	v_rcp_f32_e32 v172, v172
	v_rcp_f32_e32 v173, v173
	v_rcp_f32_e32 v174, v174
	s_nop 0
	v_mul_f32_e32 v171, v34, v171
	v_mul_f32_e32 v172, v35, v172
	v_mul_f32_e32 v173, v36, v173
	v_mul_f32_e32 v174, v37, v174
	v_mul_f32_e32 v171, v50, v171
	v_mul_f32_e32 v172, v51, v172
	v_mul_f32_e32 v173, v52, v173
	v_mul_f32_e32 v174, v53, v174
	v_cvt_pk_bf16_f32 v179, v171, v171
	v_cvt_pk_bf16_f32 v180, v172, v172
	v_cvt_pk_bf16_f32 v181, v173, v173
	v_cvt_pk_bf16_f32 v182, v174, v174
	global_store_short v162, v179, s[66:67]
	global_store_short v163, v180, s[66:67]
	global_store_short v164, v181, s[66:67]
	global_store_short v165, v182, s[66:67]
	s_add_u32 s66, s66, 0xb000
	s_addc_u32 s67, s67, 0
	v_mul_f32_e32 v171, 0xbfb8aa3b, v38
	v_mul_f32_e32 v172, 0xbfb8aa3b, v39
	v_mul_f32_e32 v173, 0xbfb8aa3b, v40
	v_mul_f32_e32 v174, 0xbfb8aa3b, v41
	v_exp_f32_e32 v171, v171
	v_exp_f32_e32 v172, v172
	v_exp_f32_e32 v173, v173
	v_exp_f32_e32 v174, v174
	s_nop 0
	v_add_f32_e32 v171, 1.0, v171
	v_add_f32_e32 v172, 1.0, v172
	v_add_f32_e32 v173, 1.0, v173
	v_add_f32_e32 v174, 1.0, v174
	v_rcp_f32_e32 v171, v171
	v_rcp_f32_e32 v172, v172
	v_rcp_f32_e32 v173, v173
	v_rcp_f32_e32 v174, v174
	s_nop 0
	v_mul_f32_e32 v171, v38, v171
	v_mul_f32_e32 v172, v39, v172
	v_mul_f32_e32 v173, v40, v173
	v_mul_f32_e32 v174, v41, v174
	v_mul_f32_e32 v171, v54, v171
	v_mul_f32_e32 v172, v55, v172
	v_mul_f32_e32 v173, v56, v173
	v_mul_f32_e32 v174, v57, v174
	v_cvt_pk_bf16_f32 v179, v171, v171
	v_cvt_pk_bf16_f32 v180, v172, v172
	v_cvt_pk_bf16_f32 v181, v173, v173
	v_cvt_pk_bf16_f32 v182, v174, v174
	global_store_short v162, v179, s[66:67]
	global_store_short v163, v180, s[66:67]
	global_store_short v164, v181, s[66:67]
	global_store_short v165, v182, s[66:67]
	s_add_u32 s66, s66, 0xb000
	s_addc_u32 s67, s67, 0
	v_mul_f32_e32 v171, 0xbfb8aa3b, v42
	v_mul_f32_e32 v172, 0xbfb8aa3b, v43
	v_mul_f32_e32 v173, 0xbfb8aa3b, v44
	v_mul_f32_e32 v174, 0xbfb8aa3b, v45
	v_exp_f32_e32 v171, v171
	v_exp_f32_e32 v172, v172
	v_exp_f32_e32 v173, v173
	v_exp_f32_e32 v174, v174
	s_nop 0
	v_add_f32_e32 v171, 1.0, v171
	v_add_f32_e32 v172, 1.0, v172
	v_add_f32_e32 v173, 1.0, v173
	v_add_f32_e32 v174, 1.0, v174
	v_rcp_f32_e32 v171, v171
	v_rcp_f32_e32 v172, v172
	v_rcp_f32_e32 v173, v173
	v_rcp_f32_e32 v174, v174
	s_nop 0
	v_mul_f32_e32 v171, v42, v171
	v_mul_f32_e32 v172, v43, v172
	v_mul_f32_e32 v173, v44, v173
	v_mul_f32_e32 v174, v45, v174
	v_mul_f32_e32 v171, v58, v171
	v_mul_f32_e32 v172, v59, v172
	v_mul_f32_e32 v173, v60, v173
	v_mul_f32_e32 v174, v61, v174
	v_cvt_pk_bf16_f32 v179, v171, v171
	v_cvt_pk_bf16_f32 v180, v172, v172
	v_cvt_pk_bf16_f32 v181, v173, v173
	v_cvt_pk_bf16_f32 v182, v174, v174
	global_store_short v162, v179, s[66:67]
	global_store_short v163, v180, s[66:67]
	global_store_short v164, v181, s[66:67]
	global_store_short v165, v182, s[66:67]
	s_add_u32 s66, s66, 0xb000
	s_addc_u32 s67, s67, 0
	v_mul_f32_e32 v171, 0xbfb8aa3b, v46
	v_mul_f32_e32 v172, 0xbfb8aa3b, v47
	v_mul_f32_e32 v173, 0xbfb8aa3b, v48
	v_mul_f32_e32 v174, 0xbfb8aa3b, v49
	v_exp_f32_e32 v171, v171
	v_exp_f32_e32 v172, v172
	v_exp_f32_e32 v173, v173
	v_exp_f32_e32 v174, v174
	s_nop 0
	v_add_f32_e32 v171, 1.0, v171
	v_add_f32_e32 v172, 1.0, v172
	v_add_f32_e32 v173, 1.0, v173
	v_add_f32_e32 v174, 1.0, v174
	v_rcp_f32_e32 v171, v171
	v_rcp_f32_e32 v172, v172
	v_rcp_f32_e32 v173, v173
	v_rcp_f32_e32 v174, v174
	s_nop 0
	v_mul_f32_e32 v171, v46, v171
	v_mul_f32_e32 v172, v47, v172
	v_mul_f32_e32 v173, v48, v173
	v_mul_f32_e32 v174, v49, v174
	v_mul_f32_e32 v171, v62, v171
	v_mul_f32_e32 v172, v63, v172
	v_mul_f32_e32 v173, v64, v173
	v_mul_f32_e32 v174, v65, v174
	v_cvt_pk_bf16_f32 v179, v171, v171
	v_cvt_pk_bf16_f32 v180, v172, v172
	v_cvt_pk_bf16_f32 v181, v173, v173
	v_cvt_pk_bf16_f32 v182, v174, v174
	global_store_short v162, v179, s[66:67]
	global_store_short v163, v180, s[66:67]
	global_store_short v164, v181, s[66:67]
	global_store_short v165, v182, s[66:67]
	s_sub_u32 s66, s66, 0x4cf80
	s_subb_u32 s67, s67, 0
	v_mul_f32_e32 v171, 0xbfb8aa3b, v66
	v_mul_f32_e32 v172, 0xbfb8aa3b, v67
	v_mul_f32_e32 v173, 0xbfb8aa3b, v68
	v_mul_f32_e32 v174, 0xbfb8aa3b, v69
	v_exp_f32_e32 v171, v171
	v_exp_f32_e32 v172, v172
	v_exp_f32_e32 v173, v173
	v_exp_f32_e32 v174, v174
	s_nop 0
	v_add_f32_e32 v171, 1.0, v171
	v_add_f32_e32 v172, 1.0, v172
	v_add_f32_e32 v173, 1.0, v173
	v_add_f32_e32 v174, 1.0, v174
	v_rcp_f32_e32 v171, v171
	v_rcp_f32_e32 v172, v172
	v_rcp_f32_e32 v173, v173
	v_rcp_f32_e32 v174, v174
	s_nop 0
	v_mul_f32_e32 v171, v66, v171
	v_mul_f32_e32 v172, v67, v172
	v_mul_f32_e32 v173, v68, v173
	v_mul_f32_e32 v174, v69, v174
	v_mul_f32_e32 v171, v82, v171
	v_mul_f32_e32 v172, v83, v172
	v_mul_f32_e32 v173, v84, v173
	v_mul_f32_e32 v174, v85, v174
	v_cvt_pk_bf16_f32 v179, v171, v171
	v_cvt_pk_bf16_f32 v180, v172, v172
	v_cvt_pk_bf16_f32 v181, v173, v173
	v_cvt_pk_bf16_f32 v182, v174, v174
	global_store_short v162, v179, s[66:67]
	global_store_short v163, v180, s[66:67]
	global_store_short v164, v181, s[66:67]
	global_store_short v165, v182, s[66:67]
	s_add_u32 s66, s66, 0xb000
	s_addc_u32 s67, s67, 0
	v_mul_f32_e32 v171, 0xbfb8aa3b, v70
	v_mul_f32_e32 v172, 0xbfb8aa3b, v71
	v_mul_f32_e32 v173, 0xbfb8aa3b, v72
	v_mul_f32_e32 v174, 0xbfb8aa3b, v73
	v_exp_f32_e32 v171, v171
	v_exp_f32_e32 v172, v172
	v_exp_f32_e32 v173, v173
	v_exp_f32_e32 v174, v174
	s_nop 0
	v_add_f32_e32 v171, 1.0, v171
	v_add_f32_e32 v172, 1.0, v172
	v_add_f32_e32 v173, 1.0, v173
	v_add_f32_e32 v174, 1.0, v174
	v_rcp_f32_e32 v171, v171
	v_rcp_f32_e32 v172, v172
	v_rcp_f32_e32 v173, v173
	v_rcp_f32_e32 v174, v174
	s_nop 0
	v_mul_f32_e32 v171, v70, v171
	v_mul_f32_e32 v172, v71, v172
	v_mul_f32_e32 v173, v72, v173
	v_mul_f32_e32 v174, v73, v174
	v_mul_f32_e32 v171, v86, v171
	v_mul_f32_e32 v172, v87, v172
	v_mul_f32_e32 v173, v88, v173
	v_mul_f32_e32 v174, v89, v174
	v_cvt_pk_bf16_f32 v179, v171, v171
	v_cvt_pk_bf16_f32 v180, v172, v172
	v_cvt_pk_bf16_f32 v181, v173, v173
	v_cvt_pk_bf16_f32 v182, v174, v174
	global_store_short v162, v179, s[66:67]
	global_store_short v163, v180, s[66:67]
	global_store_short v164, v181, s[66:67]
	global_store_short v165, v182, s[66:67]
	s_add_u32 s66, s66, 0xb000
	s_addc_u32 s67, s67, 0
	v_mul_f32_e32 v171, 0xbfb8aa3b, v74
	v_mul_f32_e32 v172, 0xbfb8aa3b, v75
	v_mul_f32_e32 v173, 0xbfb8aa3b, v76
	v_mul_f32_e32 v174, 0xbfb8aa3b, v77
	v_exp_f32_e32 v171, v171
	v_exp_f32_e32 v172, v172
	v_exp_f32_e32 v173, v173
	v_exp_f32_e32 v174, v174
	s_nop 0
	v_add_f32_e32 v171, 1.0, v171
	v_add_f32_e32 v172, 1.0, v172
	v_add_f32_e32 v173, 1.0, v173
	v_add_f32_e32 v174, 1.0, v174
	v_rcp_f32_e32 v171, v171
	v_rcp_f32_e32 v172, v172
	v_rcp_f32_e32 v173, v173
	v_rcp_f32_e32 v174, v174
	s_nop 0
	v_mul_f32_e32 v171, v74, v171
	v_mul_f32_e32 v172, v75, v172
	v_mul_f32_e32 v173, v76, v173
	v_mul_f32_e32 v174, v77, v174
	v_mul_f32_e32 v171, v90, v171
	v_mul_f32_e32 v172, v91, v172
	v_mul_f32_e32 v173, v92, v173
	v_mul_f32_e32 v174, v93, v174
	v_cvt_pk_bf16_f32 v179, v171, v171
	v_cvt_pk_bf16_f32 v180, v172, v172
	v_cvt_pk_bf16_f32 v181, v173, v173
	v_cvt_pk_bf16_f32 v182, v174, v174
	global_store_short v162, v179, s[66:67]
	global_store_short v163, v180, s[66:67]
	global_store_short v164, v181, s[66:67]
	global_store_short v165, v182, s[66:67]
	s_add_u32 s66, s66, 0xb000
	s_addc_u32 s67, s67, 0
	v_mul_f32_e32 v171, 0xbfb8aa3b, v78
	v_mul_f32_e32 v172, 0xbfb8aa3b, v79
	v_mul_f32_e32 v173, 0xbfb8aa3b, v80
	v_mul_f32_e32 v174, 0xbfb8aa3b, v81
	v_exp_f32_e32 v171, v171
	v_exp_f32_e32 v172, v172
	v_exp_f32_e32 v173, v173
	v_exp_f32_e32 v174, v174
	s_nop 0
	v_add_f32_e32 v171, 1.0, v171
	v_add_f32_e32 v172, 1.0, v172
	v_add_f32_e32 v173, 1.0, v173
	v_add_f32_e32 v174, 1.0, v174
	v_rcp_f32_e32 v171, v171
	v_rcp_f32_e32 v172, v172
	v_rcp_f32_e32 v173, v173
	v_rcp_f32_e32 v174, v174
	s_nop 0
	v_mul_f32_e32 v171, v78, v171
	v_mul_f32_e32 v172, v79, v172
	v_mul_f32_e32 v173, v80, v173
	v_mul_f32_e32 v174, v81, v174
	v_mul_f32_e32 v171, v94, v171
	v_mul_f32_e32 v172, v95, v172
	v_mul_f32_e32 v173, v96, v173
	v_mul_f32_e32 v174, v97, v174
	v_cvt_pk_bf16_f32 v179, v171, v171
	v_cvt_pk_bf16_f32 v180, v172, v172
	v_cvt_pk_bf16_f32 v181, v173, v173
	v_cvt_pk_bf16_f32 v182, v174, v174
	global_store_short v162, v179, s[66:67]
	global_store_short v163, v180, s[66:67]
	global_store_short v164, v181, s[66:67]
	global_store_short v165, v182, s[66:67]
	s_add_u32 s66, s66, 0xb000
	s_addc_u32 s67, s67, 0
	v_mul_f32_e32 v171, 0xbfb8aa3b, v98
	v_mul_f32_e32 v172, 0xbfb8aa3b, v99
	v_mul_f32_e32 v173, 0xbfb8aa3b, v100
	v_mul_f32_e32 v174, 0xbfb8aa3b, v101
	v_exp_f32_e32 v171, v171
	v_exp_f32_e32 v172, v172
	v_exp_f32_e32 v173, v173
	v_exp_f32_e32 v174, v174
	s_nop 0
	v_add_f32_e32 v171, 1.0, v171
	v_add_f32_e32 v172, 1.0, v172
	v_add_f32_e32 v173, 1.0, v173
	v_add_f32_e32 v174, 1.0, v174
	v_rcp_f32_e32 v171, v171
	v_rcp_f32_e32 v172, v172
	v_rcp_f32_e32 v173, v173
	v_rcp_f32_e32 v174, v174
	s_nop 0
	v_mul_f32_e32 v171, v98, v171
	v_mul_f32_e32 v172, v99, v172
	v_mul_f32_e32 v173, v100, v173
	v_mul_f32_e32 v174, v101, v174
	v_mul_f32_e32 v171, v114, v171
	v_mul_f32_e32 v172, v115, v172
	v_mul_f32_e32 v173, v116, v173
	v_mul_f32_e32 v174, v117, v174
	v_cvt_pk_bf16_f32 v179, v171, v171
	v_cvt_pk_bf16_f32 v180, v172, v172
	v_cvt_pk_bf16_f32 v181, v173, v173
	v_cvt_pk_bf16_f32 v182, v174, v174
	global_store_short v162, v179, s[66:67]
	global_store_short v163, v180, s[66:67]
	global_store_short v164, v181, s[66:67]
	global_store_short v165, v182, s[66:67]
	s_add_u32 s66, s66, 0xb000
	s_addc_u32 s67, s67, 0
	v_mul_f32_e32 v171, 0xbfb8aa3b, v102
	v_mul_f32_e32 v172, 0xbfb8aa3b, v103
	v_mul_f32_e32 v173, 0xbfb8aa3b, v104
	v_mul_f32_e32 v174, 0xbfb8aa3b, v105
	v_exp_f32_e32 v171, v171
	v_exp_f32_e32 v172, v172
	v_exp_f32_e32 v173, v173
	v_exp_f32_e32 v174, v174
	s_nop 0
	v_add_f32_e32 v171, 1.0, v171
	v_add_f32_e32 v172, 1.0, v172
	v_add_f32_e32 v173, 1.0, v173
	v_add_f32_e32 v174, 1.0, v174
	v_rcp_f32_e32 v171, v171
	v_rcp_f32_e32 v172, v172
	v_rcp_f32_e32 v173, v173
	v_rcp_f32_e32 v174, v174
	s_nop 0
	v_mul_f32_e32 v171, v102, v171
	v_mul_f32_e32 v172, v103, v172
	v_mul_f32_e32 v173, v104, v173
	v_mul_f32_e32 v174, v105, v174
	v_mul_f32_e32 v171, v118, v171
	v_mul_f32_e32 v172, v119, v172
	v_mul_f32_e32 v173, v120, v173
	v_mul_f32_e32 v174, v121, v174
	v_cvt_pk_bf16_f32 v179, v171, v171
	v_cvt_pk_bf16_f32 v180, v172, v172
	v_cvt_pk_bf16_f32 v181, v173, v173
	v_cvt_pk_bf16_f32 v182, v174, v174
	global_store_short v162, v179, s[66:67]
	global_store_short v163, v180, s[66:67]
	global_store_short v164, v181, s[66:67]
	global_store_short v165, v182, s[66:67]
	s_add_u32 s66, s66, 0xb000
	s_addc_u32 s67, s67, 0
	v_mul_f32_e32 v171, 0xbfb8aa3b, v106
	v_mul_f32_e32 v172, 0xbfb8aa3b, v107
	v_mul_f32_e32 v173, 0xbfb8aa3b, v108
	v_mul_f32_e32 v174, 0xbfb8aa3b, v109
	v_exp_f32_e32 v171, v171
	v_exp_f32_e32 v172, v172
	v_exp_f32_e32 v173, v173
	v_exp_f32_e32 v174, v174
	s_nop 0
	v_add_f32_e32 v171, 1.0, v171
	v_add_f32_e32 v172, 1.0, v172
	v_add_f32_e32 v173, 1.0, v173
	v_add_f32_e32 v174, 1.0, v174
	v_rcp_f32_e32 v171, v171
	v_rcp_f32_e32 v172, v172
	v_rcp_f32_e32 v173, v173
	v_rcp_f32_e32 v174, v174
	s_nop 0
	v_mul_f32_e32 v171, v106, v171
	v_mul_f32_e32 v172, v107, v172
	v_mul_f32_e32 v173, v108, v173
	v_mul_f32_e32 v174, v109, v174
	v_mul_f32_e32 v171, v122, v171
	v_mul_f32_e32 v172, v123, v172
	v_mul_f32_e32 v173, v124, v173
	v_mul_f32_e32 v174, v125, v174
	v_cvt_pk_bf16_f32 v179, v171, v171
	v_cvt_pk_bf16_f32 v180, v172, v172
	v_cvt_pk_bf16_f32 v181, v173, v173
	v_cvt_pk_bf16_f32 v182, v174, v174
	global_store_short v162, v179, s[66:67]
	global_store_short v163, v180, s[66:67]
	global_store_short v164, v181, s[66:67]
	global_store_short v165, v182, s[66:67]
	s_add_u32 s66, s66, 0xb000
	s_addc_u32 s67, s67, 0
	v_mul_f32_e32 v171, 0xbfb8aa3b, v110
	v_mul_f32_e32 v172, 0xbfb8aa3b, v111
	v_mul_f32_e32 v173, 0xbfb8aa3b, v112
	v_mul_f32_e32 v174, 0xbfb8aa3b, v113
	v_exp_f32_e32 v171, v171
	v_exp_f32_e32 v172, v172
	v_exp_f32_e32 v173, v173
	v_exp_f32_e32 v174, v174
	s_nop 0
	v_add_f32_e32 v171, 1.0, v171
	v_add_f32_e32 v172, 1.0, v172
	v_add_f32_e32 v173, 1.0, v173
	v_add_f32_e32 v174, 1.0, v174
	v_rcp_f32_e32 v171, v171
	v_rcp_f32_e32 v172, v172
	v_rcp_f32_e32 v173, v173
	v_rcp_f32_e32 v174, v174
	s_nop 0
	v_mul_f32_e32 v171, v110, v171
	v_mul_f32_e32 v172, v111, v172
	v_mul_f32_e32 v173, v112, v173
	v_mul_f32_e32 v174, v113, v174
	v_mul_f32_e32 v171, v126, v171
	v_mul_f32_e32 v172, v127, v172
	v_mul_f32_e32 v173, v128, v173
	v_mul_f32_e32 v174, v129, v174
	v_cvt_pk_bf16_f32 v179, v171, v171
	v_cvt_pk_bf16_f32 v180, v172, v172
	v_cvt_pk_bf16_f32 v181, v173, v173
	v_cvt_pk_bf16_f32 v182, v174, v174
	global_store_short v162, v179, s[66:67]
	global_store_short v163, v180, s[66:67]
	global_store_short v164, v181, s[66:67]
	global_store_short v165, v182, s[66:67]
	v_readlane_b32 s62, v246, 14
	s_nop 0
	s_add_i32 s2, s2, s62
	s_branch .Lhw_ffnup_dloop
